# post-phase row loop: counted wait vmcnt(1)->vmcnt(2) so the row's q/k stores stay in flight while waiting for the next row's loads
# baseline (speedup 1.0000x reference)
.LBB0_567:
	s_or_b64 exec, exec, s[28:29]
	v_lshlrev_b32_e32 v56, 16, v24
	v_and_b32_e32 v24, 0xffff0000, v24
	v_fma_f32 v60, v56, v56, 0
	v_lshlrev_b32_e32 v57, 16, v25
	v_fmac_f32_e32 v60, v24, v24
	v_and_b32_e32 v25, 0xffff0000, v25
	v_fmac_f32_e32 v60, v57, v57
	v_fmac_f32_e32 v60, v25, v25
	v_lshlrev_b32_e32 v58, 16, v26
	v_and_b32_e32 v26, 0xffff0000, v26
	v_fmac_f32_e32 v60, v58, v58
	v_lshlrev_b32_e32 v59, 16, v27
	v_fmac_f32_e32 v60, v26, v26
	v_and_b32_e32 v27, 0xffff0000, v27
	v_fmac_f32_e32 v60, v59, v59
	v_fmac_f32_e32 v60, v27, v27
	ds_bpermute_b32 v61, v103, v60
	s_and_b64 s[8:9], s[22:23], exec
	s_cselect_b32 s16, s47, 0
	s_waitcnt vmcnt(2)
	v_mov_b64_e32 v[74:75], v[42:43]
	v_mov_b64_e32 v[78:79], v[30:31]
	s_waitcnt lgkmcnt(0)
	v_add_f32_e32 v60, v60, v61
	ds_bpermute_b32 v61, v104, v60
	s_mov_b32 s30, s46
	v_mov_b64_e32 v[72:73], v[40:41]
	v_mov_b64_e32 v[76:77], v[28:29]
	s_waitcnt lgkmcnt(0)
	v_add_f32_e32 v60, v60, v61
	ds_bpermute_b32 v61, v105, v60
	s_waitcnt lgkmcnt(0)
	v_add_f32_e32 v60, v60, v61
	ds_bpermute_b32 v61, v106, v60
	s_waitcnt lgkmcnt(0)
	v_add_f32_e32 v60, v60, v61
	v_fmamk_f32 v60, v60, 0x3c000000, v108
	v_mul_f32_e32 v61, 0x4f800000, v60
	v_cmp_gt_f32_e32 vcc, s44, v60
	s_nop 1
	v_cndmask_b32_e32 v60, v60, v61, vcc
	v_sqrt_f32_e32 v61, v60
	s_nop 0
	v_add_u32_e32 v62, -1, v61
	v_add_u32_e32 v63, 1, v61
	v_fma_f32 v64, -v62, v61, v60
	v_fma_f32 v65, -v63, v61, v60
	v_cmp_ge_f32_e64 s[8:9], 0, v64
	s_nop 1
	v_cndmask_b32_e64 v61, v61, v62, s[8:9]
	v_cmp_lt_f32_e64 s[8:9], 0, v65
	s_nop 1
	v_cndmask_b32_e64 v61, v61, v63, s[8:9]
	v_mul_f32_e32 v62, 0x37800000, v61
	v_cndmask_b32_e32 v61, v61, v62, vcc
	v_cmp_class_f32_e32 vcc, v60, v109
	s_nop 1
	v_cndmask_b32_e32 v60, v61, v60, vcc
	v_div_scale_f32 v61, s[8:9], v60, v60, 1.0
	v_rcp_f32_e32 v62, v61
	v_div_scale_f32 v63, vcc, 1.0, v60, 1.0
	s_add_i32 s8, s16, s46
	v_fma_f32 v64, -v61, v62, 1.0
	v_fmac_f32_e32 v62, v64, v62
	v_mul_f32_e32 v64, v63, v62
	v_fma_f32 v65, -v61, v64, v63
	v_fmac_f32_e32 v64, v65, v62
	v_fma_f32 v61, -v61, v64, v63
	v_div_fmas_f32 v61, v61, v62, v64
	v_div_fixup_f32 v60, v61, v60, 1.0
	v_pk_mul_f32 v[24:25], v[60:61], v[24:25] op_sel_hi:[0,1]
	v_pk_mul_f32 v[26:27], v[60:61], v[26:27] op_sel_hi:[0,1]
	v_pk_mul_f32 v[56:57], v[60:61], v[56:57] op_sel_hi:[0,1]
	v_pk_mul_f32 v[24:25], v[22:23], v[24:25]
	v_pk_mul_f32 v[58:59], v[60:61], v[58:59] op_sel_hi:[0,1]
	v_pk_mul_f32 v[26:27], v[18:19], v[26:27]
	v_pk_mul_f32 v[56:57], v[20:21], v[56:57]
	v_pk_mul_f32 v[58:59], v[16:17], v[58:59]
	v_bfe_u32 v60, v27, 16, 1
	v_bfe_u32 v61, v26, 16, 1
	v_bfe_u32 v62, v25, 16, 1
	v_bfe_u32 v63, v24, 16, 1
	v_add3_u32 v24, v24, v63, s45
	v_add3_u32 v25, v25, v62, s45
	v_add3_u32 v26, v26, v61, s45
	v_add3_u32 v27, v27, v60, s45
	v_bfe_u32 v60, v56, 16, 1
	v_bfe_u32 v61, v57, 16, 1
	v_bfe_u32 v62, v58, 16, 1
	v_bfe_u32 v63, v59, 16, 1
	v_add3_u32 v59, v59, v63, s45
	v_add3_u32 v58, v58, v62, s45
	v_add3_u32 v57, v57, v61, s45
	v_add3_u32 v56, v56, v60, s45
	v_lshrrev_b32_e32 v56, 16, v56
	v_lshrrev_b32_e32 v57, 16, v57
	v_lshrrev_b32_e32 v58, 16, v58
	v_lshrrev_b32_e32 v59, 16, v59
	v_and_or_b32 v27, v27, s43, v59
	v_and_or_b32 v26, v26, s43, v58
	v_and_or_b32 v25, v25, s43, v57
	v_and_or_b32 v24, v24, s43, v56
	global_store_dwordx4 v[70:71], v[24:27], off offset:2560
	v_mov_b64_e32 v[58:59], v[54:55]
	v_mov_b64_e32 v[70:71], v[50:51]
	v_mov_b64_e32 v[62:63], v[46:47]
	v_mov_b64_e32 v[24:25], v[32:33]
	v_mov_b64_e32 v[66:67], v[38:39]
	s_andn2_b64 vcc, exec, s[20:21]
	v_mov_b64_e32 v[56:57], v[52:53]
	v_mov_b64_e32 v[68:69], v[48:49]
	v_mov_b64_e32 v[60:61], v[44:45]
	v_mov_b64_e32 v[26:27], v[34:35]
	v_mov_b64_e32 v[64:65], v[36:37]
	s_cbranch_vccz .LBB0_586

.LBB0_1719:
	s_or_b64 exec, exec, s[8:9]
	v_lshlrev_b32_e32 v56, 16, v24
	v_and_b32_e32 v24, 0xffff0000, v24
	v_fma_f32 v60, v56, v56, 0
	v_lshlrev_b32_e32 v57, 16, v25
	v_fmac_f32_e32 v60, v24, v24
	v_and_b32_e32 v25, 0xffff0000, v25
	v_fmac_f32_e32 v60, v57, v57
	v_fmac_f32_e32 v60, v25, v25
	v_lshlrev_b32_e32 v58, 16, v26
	v_and_b32_e32 v26, 0xffff0000, v26
	v_fmac_f32_e32 v60, v58, v58
	v_lshlrev_b32_e32 v59, 16, v27
	v_fmac_f32_e32 v60, v26, v26
	v_and_b32_e32 v27, 0xffff0000, v27
	v_fmac_f32_e32 v60, v59, v59
	v_fmac_f32_e32 v60, v27, v27
	ds_bpermute_b32 v61, v103, v60
	s_and_b64 s[8:9], s[22:23], exec
	s_cselect_b32 s16, s47, 0
	s_waitcnt vmcnt(2)
	v_mov_b64_e32 v[74:75], v[42:43]
	v_mov_b64_e32 v[78:79], v[30:31]
	s_waitcnt lgkmcnt(0)
	v_add_f32_e32 v60, v60, v61
	ds_bpermute_b32 v61, v104, v60
	s_mov_b32 s27, s46
	v_mov_b64_e32 v[72:73], v[40:41]
	v_mov_b64_e32 v[76:77], v[28:29]
	s_waitcnt lgkmcnt(0)
	v_add_f32_e32 v60, v60, v61
	ds_bpermute_b32 v61, v105, v60
	s_waitcnt lgkmcnt(0)
	v_add_f32_e32 v60, v60, v61
	ds_bpermute_b32 v61, v106, v60
	s_waitcnt lgkmcnt(0)
	v_add_f32_e32 v60, v60, v61
	v_fmamk_f32 v60, v60, 0x3c000000, v108
	v_mul_f32_e32 v61, 0x4f800000, v60
	v_cmp_gt_f32_e32 vcc, s44, v60
	s_nop 1
	v_cndmask_b32_e32 v60, v60, v61, vcc
	v_sqrt_f32_e32 v61, v60
	s_nop 0
	v_add_u32_e32 v62, -1, v61
	v_add_u32_e32 v63, 1, v61
	v_fma_f32 v64, -v62, v61, v60
	v_fma_f32 v65, -v63, v61, v60
	v_cmp_ge_f32_e64 s[8:9], 0, v64
	s_nop 1
	v_cndmask_b32_e64 v61, v61, v62, s[8:9]
	v_cmp_lt_f32_e64 s[8:9], 0, v65
	s_nop 1
	v_cndmask_b32_e64 v61, v61, v63, s[8:9]
	v_mul_f32_e32 v62, 0x37800000, v61
	v_cndmask_b32_e32 v61, v61, v62, vcc
	v_cmp_class_f32_e32 vcc, v60, v109
	s_nop 1
	v_cndmask_b32_e32 v60, v61, v60, vcc
	v_div_scale_f32 v61, s[8:9], v60, v60, 1.0
	v_rcp_f32_e32 v62, v61
	v_div_scale_f32 v63, vcc, 1.0, v60, 1.0
	s_add_i32 s8, s16, s46
	v_fma_f32 v64, -v61, v62, 1.0
	v_fmac_f32_e32 v62, v64, v62
	v_mul_f32_e32 v64, v63, v62
	v_fma_f32 v65, -v61, v64, v63
	v_fmac_f32_e32 v64, v65, v62
	v_fma_f32 v61, -v61, v64, v63
	v_div_fmas_f32 v61, v61, v62, v64
	v_div_fixup_f32 v60, v61, v60, 1.0
	v_pk_mul_f32 v[24:25], v[60:61], v[24:25] op_sel_hi:[0,1]
	v_pk_mul_f32 v[26:27], v[60:61], v[26:27] op_sel_hi:[0,1]
	v_pk_mul_f32 v[56:57], v[60:61], v[56:57] op_sel_hi:[0,1]
	v_pk_mul_f32 v[24:25], v[22:23], v[24:25]
	v_pk_mul_f32 v[58:59], v[60:61], v[58:59] op_sel_hi:[0,1]
	v_pk_mul_f32 v[26:27], v[18:19], v[26:27]
	v_pk_mul_f32 v[56:57], v[20:21], v[56:57]
	v_pk_mul_f32 v[58:59], v[16:17], v[58:59]
	v_bfe_u32 v60, v27, 16, 1
	v_bfe_u32 v61, v26, 16, 1
	v_bfe_u32 v62, v25, 16, 1
	v_bfe_u32 v63, v24, 16, 1
	v_add3_u32 v24, v24, v63, s45
	v_add3_u32 v25, v25, v62, s45
	v_add3_u32 v26, v26, v61, s45
	v_add3_u32 v27, v27, v60, s45
	v_bfe_u32 v60, v56, 16, 1
	v_bfe_u32 v61, v57, 16, 1
	v_bfe_u32 v62, v58, 16, 1
	v_bfe_u32 v63, v59, 16, 1
	v_add3_u32 v59, v59, v63, s45
	v_add3_u32 v58, v58, v62, s45
	v_add3_u32 v57, v57, v61, s45
	v_add3_u32 v56, v56, v60, s45
	v_lshrrev_b32_e32 v56, 16, v56
	v_lshrrev_b32_e32 v57, 16, v57
	v_lshrrev_b32_e32 v58, 16, v58
	v_lshrrev_b32_e32 v59, 16, v59
	v_and_or_b32 v27, v27, s43, v59
	v_and_or_b32 v26, v26, s43, v58
	v_and_or_b32 v25, v25, s43, v57
	v_and_or_b32 v24, v24, s43, v56
	global_store_dwordx4 v[70:71], v[24:27], off offset:2560
	v_mov_b64_e32 v[58:59], v[54:55]
	v_mov_b64_e32 v[70:71], v[50:51]
	v_mov_b64_e32 v[62:63], v[46:47]
	v_mov_b64_e32 v[24:25], v[32:33]
	v_mov_b64_e32 v[66:67], v[38:39]
	s_andn2_b64 vcc, exec, s[20:21]
	v_mov_b64_e32 v[56:57], v[52:53]
	v_mov_b64_e32 v[68:69], v[48:49]
	v_mov_b64_e32 v[60:61], v[44:45]
	v_mov_b64_e32 v[26:27], v[34:35]
	v_mov_b64_e32 v[64:65], v[36:37]
	s_cbranch_vccz .LBB0_1738
